# merge DMA loop: next-stage DMA issued after the first fragment reads
# baseline (speedup 1.0000x reference)
; #define MFMA(a, b, c) __builtin_amdgcn_mfma_f32_32x32x16_bf16((a), (b), (c), 0, 0, 0)
; template <int MI, int NI>
; __device__ __forceinline__ void gemm_kloop(const bf16* __restrict__ A, size_t lda, const bf16* __restrict__ Bt, size_t ldb, int K,
;                                            f16v (&acc)[MI][NI], bf16* sA, bf16* sB) {
;     ...
;   for (int kt = 0; kt < KT; ++kt) {
;     __syncthreads();
; #pragma unroll
;     for (int i = 0; i < 2 * MI; ++i) *(u4v*)(sA + (lrow + 32 * i) * 72 + lseg * 8) = ra[i];
; #pragma unroll
;     for (int i = 0; i < 2 * NI; ++i) *(u4v*)(sB + (lrow + 32 * i) * 72 + lseg * 8) = rb[i];
;     __syncthreads();
;     if (kt + 3 < KT) {
;       const int k2 = (kt + 3) << 6;
;       if (tid < 64 * MI) pfs ^= *(const unsigned*)(A + (size_t)tid * lda + k2);
;       if (tid < 64 * NI) pfs ^= *(const unsigned*)(Bt + (size_t)tid * ldb + k2);
;     }
;     if (kt + 1 < KT) {
;       const int k0 = (kt + 1) << 6;
; #pragma unroll
;       for (int i = 0; i < 2 * MI; ++i) ra[i] = *(const u4v*)(A + (size_t)(lrow + 32 * i) * lda + k0 + lseg * 8);
; #pragma unroll
;       for (int i = 0; i < 2 * NI; ++i) rb[i] = *(const u4v*)(Bt + (size_t)(lrow + 32 * i) * ldb + k0 + lseg * 8);
;     }
; #pragma unroll
;     for (int ks = 0; ks < 4; ++ks) {
;       s8v a[MI], b[NI];
; #pragma unroll
;       for (int mi = 0; mi < MI; ++mi) a[mi] = *(const s8v*)(sA + (wm * 32 * MI + mi * 32 + r) * 72 + ks * 16 + hh * 8);
; #pragma unroll
;       for (int ni = 0; ni < NI; ++ni) b[ni] = *(const s8v*)(sB + (wn * 32 * NI + ni * 32 + r) * 72 + ks * 16 + hh * 8);
; #pragma unroll
;       for (int mi = 0; mi < MI; ++mi)
; #pragma unroll
;         for (int ni = 0; ni < NI; ++ni) acc[mi][ni] = MFMA(a[mi], b[ni], acc[mi][ni]);
;     }
.Ldma_m1_loop:
	ds_read_b128 v[104:107], v140 offset:0
	ds_read_b128 v[112:115], v144 offset:0
	ds_read_b128 v[116:119], v144 offset:4096
	ds_read_b128 v[108:111], v140 offset:4096
	ds_read_b128 v[120:123], v141 offset:0
	ds_read_b128 v[128:131], v145 offset:0
	ds_read_b128 v[132:135], v145 offset:4096
	ds_read_b128 v[124:127], v141 offset:4096
	s_add_u32 m0, s96, 32768
	s_nop 0
	global_load_lds_dwordx4 v136, s[56:57] offset:0
	global_load_lds_dwordx4 v137, s[56:57] offset:1024
	global_load_lds_dwordx4 v138, s[56:57] offset:2048
	global_load_lds_dwordx4 v139, s[56:57] offset:3072
	s_add_u32 m0, s96, 49152
	s_nop 0
	global_load_lds_dwordx4 v136, s[58:59] offset:0
	global_load_lds_dwordx4 v137, s[58:59] offset:1024
	global_load_lds_dwordx4 v138, s[58:59] offset:2048
	global_load_lds_dwordx4 v139, s[58:59] offset:3072
	s_add_u32 s56, s56, 128
	s_addc_u32 s57, s57, 0
	s_add_u32 s58, s58, 128
	s_addc_u32 s59, s59, 0
	s_waitcnt lgkmcnt(6)
	v_mfma_f32_32x32x16_bf16 v[66:81], v[104:107], v[112:115], v[66:81]
	s_waitcnt lgkmcnt(5)
	v_mfma_f32_32x32x16_bf16 v[34:49], v[104:107], v[116:119], v[34:49]
	s_waitcnt lgkmcnt(4)
	v_mfma_f32_32x32x16_bf16 v[18:33], v[108:111], v[112:115], v[18:33]
	v_mfma_f32_32x32x16_bf16 v[2:17], v[108:111], v[116:119], v[2:17]
	ds_read_b128 v[104:107], v142 offset:0
	ds_read_b128 v[112:115], v146 offset:0
	ds_read_b128 v[116:119], v146 offset:4096
	ds_read_b128 v[108:111], v142 offset:4096
	s_waitcnt lgkmcnt(6)
	v_mfma_f32_32x32x16_bf16 v[66:81], v[120:123], v[128:131], v[66:81]
	s_waitcnt lgkmcnt(5)
	v_mfma_f32_32x32x16_bf16 v[34:49], v[120:123], v[132:135], v[34:49]
	s_waitcnt lgkmcnt(4)
	v_mfma_f32_32x32x16_bf16 v[18:33], v[124:127], v[128:131], v[18:33]
	v_mfma_f32_32x32x16_bf16 v[2:17], v[124:127], v[132:135], v[2:17]
	ds_read_b128 v[120:123], v143 offset:0
	ds_read_b128 v[128:131], v147 offset:0
	ds_read_b128 v[132:135], v147 offset:4096
	ds_read_b128 v[124:127], v143 offset:4096
	s_waitcnt lgkmcnt(6)
	v_mfma_f32_32x32x16_bf16 v[66:81], v[104:107], v[112:115], v[66:81]
	s_waitcnt lgkmcnt(5)
	v_mfma_f32_32x32x16_bf16 v[34:49], v[104:107], v[116:119], v[34:49]
	s_waitcnt lgkmcnt(4)
	v_mfma_f32_32x32x16_bf16 v[18:33], v[108:111], v[112:115], v[18:33]
	v_mfma_f32_32x32x16_bf16 v[2:17], v[108:111], v[116:119], v[2:17]
	s_waitcnt lgkmcnt(2)
	v_mfma_f32_32x32x16_bf16 v[66:81], v[120:123], v[128:131], v[66:81]
	s_waitcnt lgkmcnt(1)
	v_mfma_f32_32x32x16_bf16 v[34:49], v[120:123], v[132:135], v[34:49]
	s_waitcnt lgkmcnt(0)
	v_mfma_f32_32x32x16_bf16 v[18:33], v[124:127], v[128:131], v[18:33]
	v_mfma_f32_32x32x16_bf16 v[2:17], v[124:127], v[132:135], v[2:17]
	s_waitcnt vmcnt(0)
	s_barrier
	ds_read_b128 v[104:107], v140 offset:32768
	ds_read_b128 v[112:115], v144 offset:32768
	ds_read_b128 v[116:119], v144 offset:36864
	ds_read_b128 v[108:111], v140 offset:36864
	ds_read_b128 v[120:123], v141 offset:32768
	ds_read_b128 v[128:131], v145 offset:32768
	ds_read_b128 v[132:135], v145 offset:36864
	ds_read_b128 v[124:127], v141 offset:36864
	s_add_u32 m0, s96, 0
	s_nop 0
	global_load_lds_dwordx4 v136, s[56:57] offset:0
	global_load_lds_dwordx4 v137, s[56:57] offset:1024
	global_load_lds_dwordx4 v138, s[56:57] offset:2048
	global_load_lds_dwordx4 v139, s[56:57] offset:3072
	s_add_u32 m0, s96, 16384
	s_nop 0
	global_load_lds_dwordx4 v136, s[58:59] offset:0
	global_load_lds_dwordx4 v137, s[58:59] offset:1024
	global_load_lds_dwordx4 v138, s[58:59] offset:2048
	global_load_lds_dwordx4 v139, s[58:59] offset:3072
	s_add_u32 s56, s56, 128
	s_addc_u32 s57, s57, 0
	s_add_u32 s58, s58, 128
	s_addc_u32 s59, s59, 0
	s_waitcnt lgkmcnt(6)
	v_mfma_f32_32x32x16_bf16 v[66:81], v[104:107], v[112:115], v[66:81]
	s_waitcnt lgkmcnt(5)
	v_mfma_f32_32x32x16_bf16 v[34:49], v[104:107], v[116:119], v[34:49]
	s_waitcnt lgkmcnt(4)
	v_mfma_f32_32x32x16_bf16 v[18:33], v[108:111], v[112:115], v[18:33]
	v_mfma_f32_32x32x16_bf16 v[2:17], v[108:111], v[116:119], v[2:17]
	ds_read_b128 v[104:107], v142 offset:32768
	ds_read_b128 v[112:115], v146 offset:32768
	ds_read_b128 v[116:119], v146 offset:36864
	ds_read_b128 v[108:111], v142 offset:36864
	s_waitcnt lgkmcnt(6)
	v_mfma_f32_32x32x16_bf16 v[66:81], v[120:123], v[128:131], v[66:81]
	s_waitcnt lgkmcnt(5)
	v_mfma_f32_32x32x16_bf16 v[34:49], v[120:123], v[132:135], v[34:49]
	s_waitcnt lgkmcnt(4)
	v_mfma_f32_32x32x16_bf16 v[18:33], v[124:127], v[128:131], v[18:33]
	v_mfma_f32_32x32x16_bf16 v[2:17], v[124:127], v[132:135], v[2:17]
	ds_read_b128 v[120:123], v143 offset:32768
	ds_read_b128 v[128:131], v147 offset:32768
	ds_read_b128 v[132:135], v147 offset:36864
	ds_read_b128 v[124:127], v143 offset:36864
	s_waitcnt lgkmcnt(6)
	v_mfma_f32_32x32x16_bf16 v[66:81], v[104:107], v[112:115], v[66:81]
	s_waitcnt lgkmcnt(5)
	v_mfma_f32_32x32x16_bf16 v[34:49], v[104:107], v[116:119], v[34:49]
	s_waitcnt lgkmcnt(4)
	v_mfma_f32_32x32x16_bf16 v[18:33], v[108:111], v[112:115], v[18:33]
	v_mfma_f32_32x32x16_bf16 v[2:17], v[108:111], v[116:119], v[2:17]
	s_waitcnt lgkmcnt(2)
	v_mfma_f32_32x32x16_bf16 v[66:81], v[120:123], v[128:131], v[66:81]
	s_waitcnt lgkmcnt(1)
	v_mfma_f32_32x32x16_bf16 v[34:49], v[120:123], v[132:135], v[34:49]
	s_waitcnt lgkmcnt(0)
	v_mfma_f32_32x32x16_bf16 v[18:33], v[124:127], v[128:131], v[18:33]
	v_mfma_f32_32x32x16_bf16 v[2:17], v[124:127], v[132:135], v[2:17]
	s_waitcnt vmcnt(0)
	s_barrier
; #define MFMA(a, b, c) __builtin_amdgcn_mfma_f32_32x32x16_bf16((a), (b), (c), 0, 0, 0)
; template <int MI, int NI>
; __device__ __forceinline__ void gemm_kloop(const bf16* __restrict__ A, size_t lda, const bf16* __restrict__ Bt, size_t ldb, int K,
;                                            f16v (&acc)[MI][NI], bf16* sA, bf16* sB) {
;     ...
;   for (int kt = 0; kt < KT; ++kt) {
;     __syncthreads();
; #pragma unroll
;     for (int i = 0; i < 2 * MI; ++i) *(u4v*)(sA + (lrow + 32 * i) * 72 + lseg * 8) = ra[i];
; #pragma unroll
;     for (int i = 0; i < 2 * NI; ++i) *(u4v*)(sB + (lrow + 32 * i) * 72 + lseg * 8) = rb[i];
;     __syncthreads();
;     if (kt + 3 < KT) {
;       const int k2 = (kt + 3) << 6;
;       if (tid < 64 * MI) pfs ^= *(const unsigned*)(A + (size_t)tid * lda + k2);
;       if (tid < 64 * NI) pfs ^= *(const unsigned*)(Bt + (size_t)tid * ldb + k2);
;     }
;     if (kt + 1 < KT) {
;       const int k0 = (kt + 1) << 6;
; #pragma unroll
;       for (int i = 0; i < 2 * MI; ++i) ra[i] = *(const u4v*)(A + (size_t)(lrow + 32 * i) * lda + k0 + lseg * 8);
; #pragma unroll
;       for (int i = 0; i < 2 * NI; ++i) rb[i] = *(const u4v*)(Bt + (size_t)(lrow + 32 * i) * ldb + k0 + lseg * 8);
;     }
; #pragma unroll
;     for (int ks = 0; ks < 4; ++ks) {
;       s8v a[MI], b[NI];
; #pragma unroll
;       for (int mi = 0; mi < MI; ++mi) a[mi] = *(const s8v*)(sA + (wm * 32 * MI + mi * 32 + r) * 72 + ks * 16 + hh * 8);
; #pragma unroll
;       for (int ni = 0; ni < NI; ++ni) b[ni] = *(const s8v*)(sB + (wn * 32 * NI + ni * 32 + r) * 72 + ks * 16 + hh * 8);
; #pragma unroll
;       for (int mi = 0; mi < MI; ++mi)
; #pragma unroll
;         for (int ni = 0; ni < NI; ++ni) acc[mi][ni] = MFMA(a[mi], b[ni], acc[mi][ni]);
;     }
; __device__ __forceinline__ void merge_tile(const Params& p, int mt, int nt, bf16* sA, bf16* sB) {
;     ...
;     const bf16* ya = b == 0 ? p.q : (b == 1 ? p.hv : p.gog);
	s_sub_u32 s94, s94, 1
	s_cmp_lg_u32 s94, 0
	s_cbranch_scc1 .Ldma_m1_loop
	ds_read_b128 v[104:107], v140 offset:0
	ds_read_b128 v[112:115], v144 offset:0
	ds_read_b128 v[116:119], v144 offset:4096
	ds_read_b128 v[108:111], v140 offset:4096
	ds_read_b128 v[120:123], v141 offset:0
	ds_read_b128 v[128:131], v145 offset:0
	ds_read_b128 v[132:135], v145 offset:4096
	ds_read_b128 v[124:127], v141 offset:4096
	s_add_u32 m0, s96, 32768
	s_nop 0
	global_load_lds_dwordx4 v136, s[56:57] offset:0
	global_load_lds_dwordx4 v137, s[56:57] offset:1024
	global_load_lds_dwordx4 v138, s[56:57] offset:2048
	global_load_lds_dwordx4 v139, s[56:57] offset:3072
	s_add_u32 m0, s96, 49152
	s_nop 0
	global_load_lds_dwordx4 v136, s[58:59] offset:0
	global_load_lds_dwordx4 v137, s[58:59] offset:1024
	global_load_lds_dwordx4 v138, s[58:59] offset:2048
	global_load_lds_dwordx4 v139, s[58:59] offset:3072
	s_add_u32 s56, s56, 128
	s_addc_u32 s57, s57, 0
	s_add_u32 s58, s58, 128
	s_addc_u32 s59, s59, 0
	s_waitcnt lgkmcnt(6)
	v_mfma_f32_32x32x16_bf16 v[66:81], v[104:107], v[112:115], v[66:81]
	s_waitcnt lgkmcnt(5)
	v_mfma_f32_32x32x16_bf16 v[34:49], v[104:107], v[116:119], v[34:49]
	s_waitcnt lgkmcnt(4)
	v_mfma_f32_32x32x16_bf16 v[18:33], v[108:111], v[112:115], v[18:33]
	v_mfma_f32_32x32x16_bf16 v[2:17], v[108:111], v[116:119], v[2:17]
	ds_read_b128 v[104:107], v142 offset:0
	ds_read_b128 v[112:115], v146 offset:0
	ds_read_b128 v[116:119], v146 offset:4096
	ds_read_b128 v[108:111], v142 offset:4096
	s_waitcnt lgkmcnt(6)
	v_mfma_f32_32x32x16_bf16 v[66:81], v[120:123], v[128:131], v[66:81]
	s_waitcnt lgkmcnt(5)
	v_mfma_f32_32x32x16_bf16 v[34:49], v[120:123], v[132:135], v[34:49]
	s_waitcnt lgkmcnt(4)
	v_mfma_f32_32x32x16_bf16 v[18:33], v[124:127], v[128:131], v[18:33]
	v_mfma_f32_32x32x16_bf16 v[2:17], v[124:127], v[132:135], v[2:17]
	ds_read_b128 v[120:123], v143 offset:0
	ds_read_b128 v[128:131], v147 offset:0
	ds_read_b128 v[132:135], v147 offset:4096
	ds_read_b128 v[124:127], v143 offset:4096
	s_waitcnt lgkmcnt(6)
	v_mfma_f32_32x32x16_bf16 v[66:81], v[104:107], v[112:115], v[66:81]
	s_waitcnt lgkmcnt(5)
	v_mfma_f32_32x32x16_bf16 v[34:49], v[104:107], v[116:119], v[34:49]
	s_waitcnt lgkmcnt(4)
	v_mfma_f32_32x32x16_bf16 v[18:33], v[108:111], v[112:115], v[18:33]
	v_mfma_f32_32x32x16_bf16 v[2:17], v[108:111], v[116:119], v[2:17]
	s_waitcnt lgkmcnt(2)
	v_mfma_f32_32x32x16_bf16 v[66:81], v[120:123], v[128:131], v[66:81]
	s_waitcnt lgkmcnt(1)
	v_mfma_f32_32x32x16_bf16 v[34:49], v[120:123], v[132:135], v[34:49]
	s_waitcnt lgkmcnt(0)
	v_mfma_f32_32x32x16_bf16 v[18:33], v[124:127], v[128:131], v[18:33]
	v_mfma_f32_32x32x16_bf16 v[2:17], v[124:127], v[132:135], v[2:17]
	s_waitcnt vmcnt(0)
	s_barrier
	ds_read_b128 v[104:107], v140 offset:32768
	ds_read_b128 v[112:115], v144 offset:32768
	ds_read_b128 v[116:119], v144 offset:36864
	ds_read_b128 v[108:111], v140 offset:36864
	ds_read_b128 v[120:123], v141 offset:32768
	ds_read_b128 v[128:131], v145 offset:32768
	ds_read_b128 v[132:135], v145 offset:36864
	ds_read_b128 v[124:127], v141 offset:36864
	s_waitcnt lgkmcnt(6)
	v_mfma_f32_32x32x16_bf16 v[66:81], v[104:107], v[112:115], v[66:81]
	s_waitcnt lgkmcnt(5)
	v_mfma_f32_32x32x16_bf16 v[34:49], v[104:107], v[116:119], v[34:49]
	s_waitcnt lgkmcnt(4)
	v_mfma_f32_32x32x16_bf16 v[18:33], v[108:111], v[112:115], v[18:33]
	v_mfma_f32_32x32x16_bf16 v[2:17], v[108:111], v[116:119], v[2:17]
	ds_read_b128 v[104:107], v142 offset:32768
	ds_read_b128 v[112:115], v146 offset:32768
	ds_read_b128 v[116:119], v146 offset:36864
	ds_read_b128 v[108:111], v142 offset:36864
	s_waitcnt lgkmcnt(6)
	v_mfma_f32_32x32x16_bf16 v[66:81], v[120:123], v[128:131], v[66:81]
	s_waitcnt lgkmcnt(5)
	v_mfma_f32_32x32x16_bf16 v[34:49], v[120:123], v[132:135], v[34:49]
	s_waitcnt lgkmcnt(4)
	v_mfma_f32_32x32x16_bf16 v[18:33], v[124:127], v[128:131], v[18:33]
	v_mfma_f32_32x32x16_bf16 v[2:17], v[124:127], v[132:135], v[2:17]
	ds_read_b128 v[120:123], v143 offset:32768
	ds_read_b128 v[128:131], v147 offset:32768
	ds_read_b128 v[132:135], v147 offset:36864
	ds_read_b128 v[124:127], v143 offset:36864
	s_waitcnt lgkmcnt(6)
	v_mfma_f32_32x32x16_bf16 v[66:81], v[104:107], v[112:115], v[66:81]
	s_waitcnt lgkmcnt(5)
	v_mfma_f32_32x32x16_bf16 v[34:49], v[104:107], v[116:119], v[34:49]
	s_waitcnt lgkmcnt(4)
	v_mfma_f32_32x32x16_bf16 v[18:33], v[108:111], v[112:115], v[18:33]
	v_mfma_f32_32x32x16_bf16 v[2:17], v[108:111], v[116:119], v[2:17]
	s_waitcnt lgkmcnt(2)
	v_mfma_f32_32x32x16_bf16 v[66:81], v[120:123], v[128:131], v[66:81]
	s_waitcnt lgkmcnt(1)
	v_mfma_f32_32x32x16_bf16 v[34:49], v[120:123], v[132:135], v[34:49]
	s_waitcnt lgkmcnt(0)
	v_mfma_f32_32x32x16_bf16 v[18:33], v[124:127], v[128:131], v[18:33]
	v_mfma_f32_32x32x16_bf16 v[2:17], v[124:127], v[132:135], v[2:17]
	s_nop 15
	v_readlane_b32 s38, v253, 15
	s_cmp_lt_i32 s3, 1
	v_readlane_b32 s39, v253, 16
	s_cbranch_scc1 .LBB0_1074
	s_cmp_lg_u32 s3, 1
	s_mov_b64 s[38:39], -1
	s_cbranch_scc0 .LBB0_1072
	s_mov_b64 s[38:39], 0

; #define MFMA(a, b, c) __builtin_amdgcn_mfma_f32_32x32x16_bf16((a), (b), (c), 0, 0, 0)
; template <int MI, int NI>
; __device__ __forceinline__ void gemm_kloop(const bf16* __restrict__ A, size_t lda, const bf16* __restrict__ Bt, size_t ldb, int K,
;                                            f16v (&acc)[MI][NI], bf16* sA, bf16* sB) {
;     ...
;   for (int kt = 0; kt < KT; ++kt) {
;     __syncthreads();
; #pragma unroll
;     for (int i = 0; i < 2 * MI; ++i) *(u4v*)(sA + (lrow + 32 * i) * 72 + lseg * 8) = ra[i];
; #pragma unroll
;     for (int i = 0; i < 2 * NI; ++i) *(u4v*)(sB + (lrow + 32 * i) * 72 + lseg * 8) = rb[i];
;     __syncthreads();
;     if (kt + 3 < KT) {
;       const int k2 = (kt + 3) << 6;
;       if (tid < 64 * MI) pfs ^= *(const unsigned*)(A + (size_t)tid * lda + k2);
;       if (tid < 64 * NI) pfs ^= *(const unsigned*)(Bt + (size_t)tid * ldb + k2);
;     }
;     if (kt + 1 < KT) {
;       const int k0 = (kt + 1) << 6;
; #pragma unroll
;       for (int i = 0; i < 2 * MI; ++i) ra[i] = *(const u4v*)(A + (size_t)(lrow + 32 * i) * lda + k0 + lseg * 8);
; #pragma unroll
;       for (int i = 0; i < 2 * NI; ++i) rb[i] = *(const u4v*)(Bt + (size_t)(lrow + 32 * i) * ldb + k0 + lseg * 8);
;     }
; #pragma unroll
;     for (int ks = 0; ks < 4; ++ks) {
;       s8v a[MI], b[NI];
; #pragma unroll
;       for (int mi = 0; mi < MI; ++mi) a[mi] = *(const s8v*)(sA + (wm * 32 * MI + mi * 32 + r) * 72 + ks * 16 + hh * 8);
; #pragma unroll
;       for (int ni = 0; ni < NI; ++ni) b[ni] = *(const s8v*)(sB + (wn * 32 * NI + ni * 32 + r) * 72 + ks * 16 + hh * 8);
; #pragma unroll
;       for (int mi = 0; mi < MI; ++mi)
; #pragma unroll
;         for (int ni = 0; ni < NI; ++ni) acc[mi][ni] = MFMA(a[mi], b[ni], acc[mi][ni]);
;     }
.Ldma_m2_loop:
	ds_read_b128 v[130:133], v209 offset:0
	ds_read_b128 v[138:141], v213 offset:0
	ds_read_b128 v[142:145], v213 offset:4096
	ds_read_b128 v[134:137], v209 offset:4096
	ds_read_b128 v[146:149], v210 offset:0
	ds_read_b128 v[154:157], v214 offset:0
	ds_read_b128 v[158:161], v214 offset:4096
	ds_read_b128 v[150:153], v210 offset:4096
	s_add_u32 m0, s96, 32768
	s_nop 0
	global_load_lds_dwordx4 v205, s[56:57] offset:0
	global_load_lds_dwordx4 v206, s[56:57] offset:1024
	global_load_lds_dwordx4 v207, s[56:57] offset:2048
	global_load_lds_dwordx4 v208, s[56:57] offset:3072
	s_add_u32 m0, s96, 49152
	s_nop 0
	global_load_lds_dwordx4 v205, s[58:59] offset:0
	global_load_lds_dwordx4 v206, s[58:59] offset:1024
	global_load_lds_dwordx4 v207, s[58:59] offset:2048
	global_load_lds_dwordx4 v208, s[58:59] offset:3072
	s_add_u32 s56, s56, 128
	s_addc_u32 s57, s57, 0
	s_add_u32 s58, s58, 128
	s_addc_u32 s59, s59, 0
	s_waitcnt lgkmcnt(6)
	v_mfma_f32_32x32x16_bf16 v[114:129], v[130:133], v[138:141], v[114:129]
	s_waitcnt lgkmcnt(5)
	v_mfma_f32_32x32x16_bf16 v[98:113], v[130:133], v[142:145], v[98:113]
	s_waitcnt lgkmcnt(4)
	v_mfma_f32_32x32x16_bf16 v[82:97], v[134:137], v[138:141], v[82:97]
	v_mfma_f32_32x32x16_bf16 v[50:65], v[134:137], v[142:145], v[50:65]
	ds_read_b128 v[130:133], v211 offset:0
	ds_read_b128 v[138:141], v215 offset:0
	ds_read_b128 v[142:145], v215 offset:4096
	ds_read_b128 v[134:137], v211 offset:4096
	s_waitcnt lgkmcnt(6)
	v_mfma_f32_32x32x16_bf16 v[114:129], v[146:149], v[154:157], v[114:129]
	s_waitcnt lgkmcnt(5)
	v_mfma_f32_32x32x16_bf16 v[98:113], v[146:149], v[158:161], v[98:113]
	s_waitcnt lgkmcnt(4)
	v_mfma_f32_32x32x16_bf16 v[82:97], v[150:153], v[154:157], v[82:97]
	v_mfma_f32_32x32x16_bf16 v[50:65], v[150:153], v[158:161], v[50:65]
	ds_read_b128 v[146:149], v212 offset:0
	ds_read_b128 v[154:157], v216 offset:0
	ds_read_b128 v[158:161], v216 offset:4096
	ds_read_b128 v[150:153], v212 offset:4096
	s_waitcnt lgkmcnt(6)
	v_mfma_f32_32x32x16_bf16 v[114:129], v[130:133], v[138:141], v[114:129]
	s_waitcnt lgkmcnt(5)
	v_mfma_f32_32x32x16_bf16 v[98:113], v[130:133], v[142:145], v[98:113]
	s_waitcnt lgkmcnt(4)
	v_mfma_f32_32x32x16_bf16 v[82:97], v[134:137], v[138:141], v[82:97]
	v_mfma_f32_32x32x16_bf16 v[50:65], v[134:137], v[142:145], v[50:65]
	s_waitcnt lgkmcnt(2)
	v_mfma_f32_32x32x16_bf16 v[114:129], v[146:149], v[154:157], v[114:129]
	s_waitcnt lgkmcnt(1)
	v_mfma_f32_32x32x16_bf16 v[98:113], v[146:149], v[158:161], v[98:113]
	s_waitcnt lgkmcnt(0)
	v_mfma_f32_32x32x16_bf16 v[82:97], v[150:153], v[154:157], v[82:97]
	v_mfma_f32_32x32x16_bf16 v[50:65], v[150:153], v[158:161], v[50:65]
	s_waitcnt vmcnt(0)
	s_barrier
	ds_read_b128 v[130:133], v209 offset:32768
	ds_read_b128 v[138:141], v213 offset:32768
	ds_read_b128 v[142:145], v213 offset:36864
	ds_read_b128 v[134:137], v209 offset:36864
	ds_read_b128 v[146:149], v210 offset:32768
	ds_read_b128 v[154:157], v214 offset:32768
	ds_read_b128 v[158:161], v214 offset:36864
	ds_read_b128 v[150:153], v210 offset:36864
	s_add_u32 m0, s96, 0
	s_nop 0
	global_load_lds_dwordx4 v205, s[56:57] offset:0
	global_load_lds_dwordx4 v206, s[56:57] offset:1024
	global_load_lds_dwordx4 v207, s[56:57] offset:2048
	global_load_lds_dwordx4 v208, s[56:57] offset:3072
	s_add_u32 m0, s96, 16384
	s_nop 0
	global_load_lds_dwordx4 v205, s[58:59] offset:0
	global_load_lds_dwordx4 v206, s[58:59] offset:1024
	global_load_lds_dwordx4 v207, s[58:59] offset:2048
	global_load_lds_dwordx4 v208, s[58:59] offset:3072
	s_add_u32 s56, s56, 128
	s_addc_u32 s57, s57, 0
	s_add_u32 s58, s58, 128
	s_addc_u32 s59, s59, 0
	s_waitcnt lgkmcnt(6)
	v_mfma_f32_32x32x16_bf16 v[114:129], v[130:133], v[138:141], v[114:129]
	s_waitcnt lgkmcnt(5)
	v_mfma_f32_32x32x16_bf16 v[98:113], v[130:133], v[142:145], v[98:113]
	s_waitcnt lgkmcnt(4)
	v_mfma_f32_32x32x16_bf16 v[82:97], v[134:137], v[138:141], v[82:97]
	v_mfma_f32_32x32x16_bf16 v[50:65], v[134:137], v[142:145], v[50:65]
	ds_read_b128 v[130:133], v211 offset:32768
	ds_read_b128 v[138:141], v215 offset:32768
	ds_read_b128 v[142:145], v215 offset:36864
	ds_read_b128 v[134:137], v211 offset:36864
	s_waitcnt lgkmcnt(6)
	v_mfma_f32_32x32x16_bf16 v[114:129], v[146:149], v[154:157], v[114:129]
	s_waitcnt lgkmcnt(5)
	v_mfma_f32_32x32x16_bf16 v[98:113], v[146:149], v[158:161], v[98:113]
	s_waitcnt lgkmcnt(4)
	v_mfma_f32_32x32x16_bf16 v[82:97], v[150:153], v[154:157], v[82:97]
	v_mfma_f32_32x32x16_bf16 v[50:65], v[150:153], v[158:161], v[50:65]
	ds_read_b128 v[146:149], v212 offset:32768
	ds_read_b128 v[154:157], v216 offset:32768
	ds_read_b128 v[158:161], v216 offset:36864
	ds_read_b128 v[150:153], v212 offset:36864
	s_waitcnt lgkmcnt(6)
	v_mfma_f32_32x32x16_bf16 v[114:129], v[130:133], v[138:141], v[114:129]
	s_waitcnt lgkmcnt(5)
	v_mfma_f32_32x32x16_bf16 v[98:113], v[130:133], v[142:145], v[98:113]
	s_waitcnt lgkmcnt(4)
	v_mfma_f32_32x32x16_bf16 v[82:97], v[134:137], v[138:141], v[82:97]
	v_mfma_f32_32x32x16_bf16 v[50:65], v[134:137], v[142:145], v[50:65]
	s_waitcnt lgkmcnt(2)
	v_mfma_f32_32x32x16_bf16 v[114:129], v[146:149], v[154:157], v[114:129]
	s_waitcnt lgkmcnt(1)
	v_mfma_f32_32x32x16_bf16 v[98:113], v[146:149], v[158:161], v[98:113]
	s_waitcnt lgkmcnt(0)
	v_mfma_f32_32x32x16_bf16 v[82:97], v[150:153], v[154:157], v[82:97]
	v_mfma_f32_32x32x16_bf16 v[50:65], v[150:153], v[158:161], v[50:65]
	s_waitcnt vmcnt(0)
	s_barrier
	s_sub_u32 s94, s94, 1
	s_cmp_lg_u32 s94, 0
	s_cbranch_scc1 .Ldma_m2_loop
; #define MFMA(a, b, c) __builtin_amdgcn_mfma_f32_32x32x16_bf16((a), (b), (c), 0, 0, 0)
; template <int MI, int NI>
; __device__ __forceinline__ void gemm_kloop(const bf16* __restrict__ A, size_t lda, const bf16* __restrict__ Bt, size_t ldb, int K,
;                                            f16v (&acc)[MI][NI], bf16* sA, bf16* sB) {
;     ...
;   for (int kt = 0; kt < KT; ++kt) {
;     __syncthreads();
; #pragma unroll
;     for (int i = 0; i < 2 * MI; ++i) *(u4v*)(sA + (lrow + 32 * i) * 72 + lseg * 8) = ra[i];
; #pragma unroll
;     for (int i = 0; i < 2 * NI; ++i) *(u4v*)(sB + (lrow + 32 * i) * 72 + lseg * 8) = rb[i];
;     __syncthreads();
;     if (kt + 3 < KT) {
;       const int k2 = (kt + 3) << 6;
;       if (tid < 64 * MI) pfs ^= *(const unsigned*)(A + (size_t)tid * lda + k2);
;       if (tid < 64 * NI) pfs ^= *(const unsigned*)(Bt + (size_t)tid * ldb + k2);
;     }
;     if (kt + 1 < KT) {
;       const int k0 = (kt + 1) << 6;
; #pragma unroll
;       for (int i = 0; i < 2 * MI; ++i) ra[i] = *(const u4v*)(A + (size_t)(lrow + 32 * i) * lda + k0 + lseg * 8);
; #pragma unroll
;       for (int i = 0; i < 2 * NI; ++i) rb[i] = *(const u4v*)(Bt + (size_t)(lrow + 32 * i) * ldb + k0 + lseg * 8);
;     }
; #pragma unroll
;     for (int ks = 0; ks < 4; ++ks) {
;       s8v a[MI], b[NI];
; #pragma unroll
;       for (int mi = 0; mi < MI; ++mi) a[mi] = *(const s8v*)(sA + (wm * 32 * MI + mi * 32 + r) * 72 + ks * 16 + hh * 8);
; #pragma unroll
;       for (int ni = 0; ni < NI; ++ni) b[ni] = *(const s8v*)(sB + (wn * 32 * NI + ni * 32 + r) * 72 + ks * 16 + hh * 8);
; #pragma unroll
;       for (int mi = 0; mi < MI; ++mi)
; #pragma unroll
;         for (int ni = 0; ni < NI; ++ni) acc[mi][ni] = MFMA(a[mi], b[ni], acc[mi][ni]);
;     }
	ds_read_b128 v[130:133], v209 offset:0
	ds_read_b128 v[138:141], v213 offset:0
	ds_read_b128 v[142:145], v213 offset:4096
	ds_read_b128 v[134:137], v209 offset:4096
	ds_read_b128 v[146:149], v210 offset:0
	ds_read_b128 v[154:157], v214 offset:0
	ds_read_b128 v[158:161], v214 offset:4096
	ds_read_b128 v[150:153], v210 offset:4096
	s_add_u32 m0, s96, 32768
	s_nop 0
	global_load_lds_dwordx4 v205, s[56:57] offset:0
	global_load_lds_dwordx4 v206, s[56:57] offset:1024
	global_load_lds_dwordx4 v207, s[56:57] offset:2048
	global_load_lds_dwordx4 v208, s[56:57] offset:3072
	s_add_u32 m0, s96, 49152
	s_nop 0
	global_load_lds_dwordx4 v205, s[58:59] offset:0
	global_load_lds_dwordx4 v206, s[58:59] offset:1024
	global_load_lds_dwordx4 v207, s[58:59] offset:2048
	global_load_lds_dwordx4 v208, s[58:59] offset:3072
	s_add_u32 s56, s56, 128
	s_addc_u32 s57, s57, 0
	s_add_u32 s58, s58, 128
	s_addc_u32 s59, s59, 0
	s_waitcnt lgkmcnt(6)
	v_mfma_f32_32x32x16_bf16 v[114:129], v[130:133], v[138:141], v[114:129]
	s_waitcnt lgkmcnt(5)
	v_mfma_f32_32x32x16_bf16 v[98:113], v[130:133], v[142:145], v[98:113]
	s_waitcnt lgkmcnt(4)
	v_mfma_f32_32x32x16_bf16 v[82:97], v[134:137], v[138:141], v[82:97]
	v_mfma_f32_32x32x16_bf16 v[50:65], v[134:137], v[142:145], v[50:65]
	ds_read_b128 v[130:133], v211 offset:0
	ds_read_b128 v[138:141], v215 offset:0
	ds_read_b128 v[142:145], v215 offset:4096
	ds_read_b128 v[134:137], v211 offset:4096
	s_waitcnt lgkmcnt(6)
	v_mfma_f32_32x32x16_bf16 v[114:129], v[146:149], v[154:157], v[114:129]
	s_waitcnt lgkmcnt(5)
	v_mfma_f32_32x32x16_bf16 v[98:113], v[146:149], v[158:161], v[98:113]
	s_waitcnt lgkmcnt(4)
	v_mfma_f32_32x32x16_bf16 v[82:97], v[150:153], v[154:157], v[82:97]
	v_mfma_f32_32x32x16_bf16 v[50:65], v[150:153], v[158:161], v[50:65]
	ds_read_b128 v[146:149], v212 offset:0
	ds_read_b128 v[154:157], v216 offset:0
	ds_read_b128 v[158:161], v216 offset:4096
	ds_read_b128 v[150:153], v212 offset:4096
	s_waitcnt lgkmcnt(6)
	v_mfma_f32_32x32x16_bf16 v[114:129], v[130:133], v[138:141], v[114:129]
	s_waitcnt lgkmcnt(5)
	v_mfma_f32_32x32x16_bf16 v[98:113], v[130:133], v[142:145], v[98:113]
	s_waitcnt lgkmcnt(4)
	v_mfma_f32_32x32x16_bf16 v[82:97], v[134:137], v[138:141], v[82:97]
	v_mfma_f32_32x32x16_bf16 v[50:65], v[134:137], v[142:145], v[50:65]
	s_waitcnt lgkmcnt(2)
	v_mfma_f32_32x32x16_bf16 v[114:129], v[146:149], v[154:157], v[114:129]
	s_waitcnt lgkmcnt(1)
	v_mfma_f32_32x32x16_bf16 v[98:113], v[146:149], v[158:161], v[98:113]
	s_waitcnt lgkmcnt(0)
	v_mfma_f32_32x32x16_bf16 v[82:97], v[150:153], v[154:157], v[82:97]
	v_mfma_f32_32x32x16_bf16 v[50:65], v[150:153], v[158:161], v[50:65]
	s_waitcnt vmcnt(0)
	s_barrier
	ds_read_b128 v[130:133], v209 offset:32768
	ds_read_b128 v[138:141], v213 offset:32768
	ds_read_b128 v[142:145], v213 offset:36864
	ds_read_b128 v[134:137], v209 offset:36864
	ds_read_b128 v[146:149], v210 offset:32768
	ds_read_b128 v[154:157], v214 offset:32768
	ds_read_b128 v[158:161], v214 offset:36864
	ds_read_b128 v[150:153], v210 offset:36864
	s_waitcnt lgkmcnt(6)
	v_mfma_f32_32x32x16_bf16 v[114:129], v[130:133], v[138:141], v[114:129]
	s_waitcnt lgkmcnt(5)
	v_mfma_f32_32x32x16_bf16 v[98:113], v[130:133], v[142:145], v[98:113]
	s_waitcnt lgkmcnt(4)
	v_mfma_f32_32x32x16_bf16 v[82:97], v[134:137], v[138:141], v[82:97]
	v_mfma_f32_32x32x16_bf16 v[50:65], v[134:137], v[142:145], v[50:65]
	ds_read_b128 v[130:133], v211 offset:32768
	ds_read_b128 v[138:141], v215 offset:32768
	ds_read_b128 v[142:145], v215 offset:36864
	ds_read_b128 v[134:137], v211 offset:36864
	s_waitcnt lgkmcnt(6)
	v_mfma_f32_32x32x16_bf16 v[114:129], v[146:149], v[154:157], v[114:129]
	s_waitcnt lgkmcnt(5)
	v_mfma_f32_32x32x16_bf16 v[98:113], v[146:149], v[158:161], v[98:113]
	s_waitcnt lgkmcnt(4)
	v_mfma_f32_32x32x16_bf16 v[82:97], v[150:153], v[154:157], v[82:97]
	v_mfma_f32_32x32x16_bf16 v[50:65], v[150:153], v[158:161], v[50:65]
	ds_read_b128 v[146:149], v212 offset:32768
	ds_read_b128 v[154:157], v216 offset:32768
	ds_read_b128 v[158:161], v216 offset:36864
	ds_read_b128 v[150:153], v212 offset:36864
	s_waitcnt lgkmcnt(6)
	v_mfma_f32_32x32x16_bf16 v[114:129], v[130:133], v[138:141], v[114:129]
	s_waitcnt lgkmcnt(5)
	v_mfma_f32_32x32x16_bf16 v[98:113], v[130:133], v[142:145], v[98:113]
	s_waitcnt lgkmcnt(4)
	v_mfma_f32_32x32x16_bf16 v[82:97], v[134:137], v[138:141], v[82:97]
	v_mfma_f32_32x32x16_bf16 v[50:65], v[134:137], v[142:145], v[50:65]
	s_waitcnt lgkmcnt(2)
	v_mfma_f32_32x32x16_bf16 v[114:129], v[146:149], v[154:157], v[114:129]
	s_waitcnt lgkmcnt(1)
	v_mfma_f32_32x32x16_bf16 v[98:113], v[146:149], v[158:161], v[98:113]
	s_waitcnt lgkmcnt(0)
; __device__ __forceinline__ unsigned pack2(float a, float b) { f2_t f = {a, b}; return __builtin_bit_cast(unsigned, __builtin_convertvector(f, bf2_t)); }
; __device__ __forceinline__ float sigmoidf_(float x) { return __builtin_amdgcn_rcpf(1.f + fexp(-x)); }
; __device__ __forceinline__ void merge_tile(const Params& p, int mt, int nt, bf16* sA, bf16* sB) {
;     ...
; #pragma unroll
;       for (int mi = 0; mi < 2; ++mi)
; #pragma unroll
;         for (int ni = 0; ni < 2; ++ni)
; #pragma unroll
;           for (int e = 0; e < 8; ++e) sg[mi][ni][e] = pack2(sigmoidf_(ag[mi][ni][2 * e]), sigmoidf_(ag[mi][ni][2 * e + 1]));
	v_mfma_f32_32x32x16_bf16 v[82:97], v[150:153], v[154:157], v[82:97]
	v_mfma_f32_32x32x16_bf16 v[50:65], v[150:153], v[158:161], v[50:65]
	s_nop 15
	v_mul_f32_e32 v36, 0xbfb8aa3b, v36
	v_mul_f32_e32 v37, 0xbfb8aa3b, v37
	v_mul_f32_e32 v66, 0xbfb8aa3b, v66
	v_mul_f32_e32 v67, 0xbfb8aa3b, v67
	v_exp_f32_e32 v36, v36
	v_exp_f32_e32 v37, v37
	v_exp_f32_e32 v66, v66
	v_exp_f32_e32 v67, v67
	v_add_f32_e32 v36, 1.0, v36
	v_add_f32_e32 v37, 1.0, v37
	v_mul_f32_e32 v38, 0xbfb8aa3b, v38
	v_mul_f32_e32 v39, 0xbfb8aa3b, v39
	v_add_f32_e32 v66, 1.0, v66
	v_add_f32_e32 v67, 1.0, v67
	v_mul_f32_e32 v68, 0xbfb8aa3b, v68
	v_mul_f32_e32 v69, 0xbfb8aa3b, v69
	v_rcp_f32_e32 v36, v36
	v_rcp_f32_e32 v37, v37
	v_exp_f32_e32 v38, v38
	v_exp_f32_e32 v39, v39
	v_rcp_f32_e32 v66, v66
	v_rcp_f32_e32 v67, v67
	v_exp_f32_e32 v68, v68
	v_exp_f32_e32 v69, v69
	v_cvt_pk_bf16_f32 v36, v36, v37
	v_add_f32_e32 v37, 1.0, v38
	v_add_f32_e32 v38, 1.0, v39
	v_mul_f32_e32 v39, 0xbfb8aa3b, v40
	v_mul_f32_e32 v40, 0xbfb8aa3b, v41
	v_cvt_pk_bf16_f32 v66, v66, v67
	v_add_f32_e32 v67, 1.0, v68
	v_add_f32_e32 v68, 1.0, v69
	v_mul_f32_e32 v69, 0xbfb8aa3b, v70
	v_mul_f32_e32 v70, 0xbfb8aa3b, v71
	v_rcp_f32_e32 v37, v37
	v_rcp_f32_e32 v38, v38
	v_exp_f32_e32 v39, v39
	v_exp_f32_e32 v40, v40
	v_rcp_f32_e32 v67, v67
	v_rcp_f32_e32 v68, v68
	v_exp_f32_e32 v69, v69
	v_exp_f32_e32 v70, v70
	v_cvt_pk_bf16_f32 v37, v37, v38
	v_add_f32_e32 v38, 1.0, v39
	v_add_f32_e32 v39, 1.0, v40
	v_mul_f32_e32 v40, 0xbfb8aa3b, v42
	v_mul_f32_e32 v41, 0xbfb8aa3b, v43
	v_cvt_pk_bf16_f32 v67, v67, v68
	v_add_f32_e32 v68, 1.0, v69
	v_add_f32_e32 v69, 1.0, v70
	v_mul_f32_e32 v70, 0xbfb8aa3b, v72
	v_mul_f32_e32 v71, 0xbfb8aa3b, v73
	v_rcp_f32_e32 v38, v38
	v_rcp_f32_e32 v39, v39
	v_exp_f32_e32 v40, v40
	v_exp_f32_e32 v41, v41
	v_rcp_f32_e32 v68, v68
	v_rcp_f32_e32 v69, v69
	v_exp_f32_e32 v70, v70
	v_exp_f32_e32 v71, v71
	v_cvt_pk_bf16_f32 v38, v38, v39
	v_add_f32_e32 v39, 1.0, v40
	v_add_f32_e32 v40, 1.0, v41
	v_mul_f32_e32 v41, 0xbfb8aa3b, v44
	v_mul_f32_e32 v42, 0xbfb8aa3b, v45
	v_cvt_pk_bf16_f32 v68, v68, v69
	v_add_f32_e32 v69, 1.0, v70
	v_add_f32_e32 v70, 1.0, v71
	v_mul_f32_e32 v71, 0xbfb8aa3b, v74
	v_mul_f32_e32 v72, 0xbfb8aa3b, v75
	v_rcp_f32_e32 v39, v39
	v_rcp_f32_e32 v40, v40
	v_exp_f32_e32 v41, v41
	v_exp_f32_e32 v42, v42
	v_rcp_f32_e32 v69, v69
	v_rcp_f32_e32 v70, v70
	v_exp_f32_e32 v71, v71
	v_exp_f32_e32 v72, v72
	v_mul_f32_e32 v20, 0xbfb8aa3b, v20
	v_mul_f32_e32 v21, 0xbfb8aa3b, v21
	v_cvt_pk_bf16_f32 v39, v39, v40
	v_add_f32_e32 v40, 1.0, v41
	v_add_f32_e32 v41, 1.0, v42
	v_mul_f32_e32 v42, 0xbfb8aa3b, v46
	v_mul_f32_e32 v43, 0xbfb8aa3b, v47
	v_exp_f32_e32 v20, v20
	v_exp_f32_e32 v21, v21
	v_cvt_pk_bf16_f32 v69, v69, v70
	v_add_f32_e32 v70, 1.0, v71
	v_add_f32_e32 v71, 1.0, v72
	v_mul_f32_e32 v72, 0xbfb8aa3b, v76
	v_mul_f32_e32 v73, 0xbfb8aa3b, v77
	v_rcp_f32_e32 v40, v40
	v_rcp_f32_e32 v41, v41
	v_exp_f32_e32 v42, v42
	v_exp_f32_e32 v43, v43
	v_rcp_f32_e32 v70, v70
	v_rcp_f32_e32 v71, v71
	v_exp_f32_e32 v72, v72
	v_exp_f32_e32 v73, v73
	v_add_f32_e32 v20, 1.0, v20
	v_add_f32_e32 v21, 1.0, v21
	v_mul_f32_e32 v22, 0xbfb8aa3b, v22
	v_mul_f32_e32 v23, 0xbfb8aa3b, v23
	v_cvt_pk_bf16_f32 v40, v40, v41
	v_add_f32_e32 v41, 1.0, v42
	v_add_f32_e32 v42, 1.0, v43
	v_mul_f32_e32 v43, 0xbfb8aa3b, v48
	v_mul_f32_e32 v44, 0xbfb8aa3b, v49
	v_rcp_f32_e32 v20, v20
	v_rcp_f32_e32 v21, v21
	v_exp_f32_e32 v22, v22
	v_exp_f32_e32 v23, v23
	v_cvt_pk_bf16_f32 v70, v70, v71
	v_add_f32_e32 v71, 1.0, v72
	v_add_f32_e32 v72, 1.0, v73
	v_mul_f32_e32 v73, 0xbfb8aa3b, v78
	v_mul_f32_e32 v74, 0xbfb8aa3b, v79
	v_rcp_f32_e32 v41, v41
	v_rcp_f32_e32 v42, v42
	v_exp_f32_e32 v43, v43
	v_exp_f32_e32 v44, v44
	v_rcp_f32_e32 v71, v71
	v_rcp_f32_e32 v72, v72
	v_exp_f32_e32 v73, v73
	v_exp_f32_e32 v74, v74
	v_mul_f32_e32 v18, 0xbfb8aa3b, v18
	v_cvt_pk_bf16_f32 v20, v20, v21
	v_add_f32_e32 v21, 1.0, v22
	v_add_f32_e32 v22, 1.0, v23
	v_mul_f32_e32 v23, 0xbfb8aa3b, v24
	v_mul_f32_e32 v24, 0xbfb8aa3b, v25
	v_cvt_pk_bf16_f32 v41, v41, v42
	v_add_f32_e32 v42, 1.0, v43
	v_add_f32_e32 v43, 1.0, v44
	v_exp_f32_e32 v44, v18
	v_mul_f32_e32 v18, 0xbfb8aa3b, v19
	v_rcp_f32_e32 v21, v21
	v_rcp_f32_e32 v22, v22
	v_exp_f32_e32 v23, v23
	v_exp_f32_e32 v24, v24
	v_cvt_pk_bf16_f32 v71, v71, v72
	v_add_f32_e32 v72, 1.0, v73
	v_add_f32_e32 v73, 1.0, v74
	v_mul_f32_e32 v74, 0xbfb8aa3b, v80
	v_mul_f32_e32 v75, 0xbfb8aa3b, v81
	v_rcp_f32_e32 v42, v42
	v_rcp_f32_e32 v43, v43
	v_exp_f32_e32 v19, v18
	v_rcp_f32_e32 v72, v72
	v_rcp_f32_e32 v73, v73
	v_exp_f32_e32 v74, v74
	v_exp_f32_e32 v75, v75
	v_cvt_pk_bf16_f32 v21, v21, v22
	v_add_f32_e32 v22, 1.0, v23
	v_add_f32_e32 v23, 1.0, v24
	v_mul_f32_e32 v24, 0xbfb8aa3b, v26
	v_mul_f32_e32 v25, 0xbfb8aa3b, v27
	v_mul_f32_e32 v34, 0xbfb8aa3b, v34
	v_cvt_pk_bf16_f32 v18, v42, v43
	v_add_f32_e32 v42, 1.0, v44
	v_add_f32_e32 v19, 1.0, v19
	v_rcp_f32_e32 v22, v22
	v_rcp_f32_e32 v23, v23
	v_exp_f32_e32 v24, v24
	v_exp_f32_e32 v25, v25
	v_cvt_pk_bf16_f32 v72, v72, v73
	v_add_f32_e32 v73, 1.0, v74
	v_add_f32_e32 v74, 1.0, v75
	v_exp_f32_e32 v75, v34
	v_mul_f32_e32 v34, 0xbfb8aa3b, v35
	v_rcp_f32_e32 v42, v42
	v_rcp_f32_e32 v19, v19
	v_rcp_f32_e32 v73, v73
	v_rcp_f32_e32 v74, v74
	v_exp_f32_e32 v35, v34
	v_cvt_pk_bf16_f32 v22, v22, v23
	v_add_f32_e32 v23, 1.0, v24
	v_add_f32_e32 v24, 1.0, v25
	v_cvt_pk_bf16_f32 v19, v42, v19
	v_rcp_f32_e32 v42, v24
	v_mul_f32_e32 v24, 0xbfb8aa3b, v28
	v_cvt_pk_bf16_f32 v34, v73, v74
	v_add_f32_e32 v73, 1.0, v75
	v_add_f32_e32 v35, 1.0, v35
	v_exp_f32_e32 v28, v24
	v_rcp_f32_e32 v73, v73
	v_rcp_f32_e32 v35, v35
	v_rcp_f32_e32 v23, v23
	v_add_f32_e32 v28, 1.0, v28
	v_cvt_pk_bf16_f32 v35, v73, v35
; __device__ __forceinline__ unsigned pack2(float a, float b) { f2_t f = {a, b}; return __builtin_bit_cast(unsigned, __builtin_convertvector(f, bf2_t)); }
; __device__ __forceinline__ float sigmoidf_(float x) { return __builtin_amdgcn_rcpf(1.f + fexp(-x)); }
; #define ZERO_ACC(acc, MI_, NI_)                 \
;   _Pragma("unroll") for (int mi = 0; mi < MI_; ++mi) \
;   _Pragma("unroll") for (int ni = 0; ni < NI_; ++ni) \
;   _Pragma("unroll") for (int e = 0; e < 16; ++e) acc[mi][ni][e] = 0.f;
; __device__ __forceinline__ void merge_tile(const Params& p, int mt, int nt, bf16* sA, bf16* sB) {
;     ...
;       for (int mi = 0; mi < 2; ++mi)
; #pragma unroll
;         for (int ni = 0; ni < 2; ++ni)
; #pragma unroll
;           for (int e = 0; e < 8; ++e) sg[mi][ni][e] = pack2(sigmoidf_(ag[mi][ni][2 * e]), sigmoidf_(ag[mi][ni][2 * e + 1]));
;     }
;     f16v ap[2][2];
;     ZERO_ACC(ap, 2, 2)
;     const bf16* ya = b == 0 ? p.q : (b == 1 ? p.hv : p.gog);
;     gemm_kloop<2, 2>(ya + (size_t)m0 * 512, 512, p.WbT + (size_t)(b * 1024 + n0) * 512, 512, 512, ap, sA, sB);
; #pragma unroll
;     for (int mi = 0; mi < 2; ++mi)
; #pragma unroll
;       for (int ni = 0; ni < 2; ++ni)
; #pragma unroll
;         for (int e = 0; e < 8; ++e) {
;           const float v0 = __uint_as_float(mg[mi][ni][e] << 16) + __uint_as_float(sg[mi][ni][e] << 16) * ap[mi][ni][2 * e];
;           const float v1 = __uint_as_float(mg[mi][ni][e] & 0xffff0000u) + __uint_as_float(sg[mi][ni][e] & 0xffff0000u) * ap[mi][ni][2 * e + 1];
;           mg[mi][ni][e] = pack2(v0, v1);
;         }
	v_rcp_f32_e32 v73, v28
	v_mul_f32_e32 v28, 0xbfb8aa3b, v29
	v_exp_f32_e32 v28, v28
	v_cvt_pk_bf16_f32 v23, v23, v42
	v_add_f32_e32 v134, 1.0, v28
	v_mul_f32_e32 v28, 0xbfb8aa3b, v30
	v_mul_f32_e32 v32, 0xbfb8aa3b, v32
	v_mul_f32_e32 v33, 0xbfb8aa3b, v33
	v_exp_f32_e32 v135, v28
	v_mul_f32_e32 v136, 0xbfb8aa3b, v31
	v_exp_f32_e32 v32, v32
	v_exp_f32_e32 v33, v33
	v_mul_f32_e32 v2, 0xbfb8aa3b, v2
	v_add_f32_e32 v32, 1.0, v32
	v_exp_f32_e32 v2, v2
	v_mul_f32_e32 v3, 0xbfb8aa3b, v3
	v_exp_f32_e32 v3, v3
	v_rcp_f32_e32 v134, v134
	v_add_f32_e32 v2, 1.0, v2
	v_mul_f32_e32 v12, 0xbfb8aa3b, v12
	v_add_f32_e32 v29, 1.0, v33
	v_rcp_f32_e32 v28, v32
	v_rcp_f32_e32 v29, v29
	v_cvt_pk_bf16_f32 v73, v73, v134
	s_add_i32 s3, s3, 1
	s_add_u32 s28, s28, 0x200000
	v_cvt_pk_bf16_f32 v32, v28, v29
	v_rcp_f32_e32 v28, v2
	v_add_f32_e32 v2, 1.0, v3
	v_mul_f32_e32 v3, 0xbfb8aa3b, v4
	v_exp_f32_e32 v3, v3
	v_mul_f32_e32 v4, 0xbfb8aa3b, v5
	v_exp_f32_e32 v4, v4
	v_rcp_f32_e32 v29, v2
	v_add_f32_e32 v2, 1.0, v3
	v_mul_f32_e32 v3, 0xbfb8aa3b, v6
	v_rcp_f32_e32 v30, v2
	v_exp_f32_e32 v24, v136
	v_add_f32_e32 v25, 1.0, v135
	v_rcp_f32_e32 v135, v25
	v_add_f32_e32 v2, 1.0, v4
	v_add_f32_e32 v24, 1.0, v24
	v_rcp_f32_e32 v136, v24
	v_exp_f32_e32 v3, v3
	v_mul_f32_e32 v4, 0xbfb8aa3b, v7
	v_exp_f32_e32 v4, v4
	v_rcp_f32_e32 v6, v2
	v_add_f32_e32 v2, 1.0, v3
	v_rcp_f32_e32 v7, v2
	v_add_f32_e32 v31, 1.0, v4
	v_rcp_f32_e32 v31, v31
	v_cvt_pk_bf16_f32 v33, v28, v29
	v_cvt_pk_bf16_f32 v78, v30, v6
	v_mul_f32_e32 v6, 0xbfb8aa3b, v8
	v_cvt_pk_bf16_f32 v79, v7, v31
	v_exp_f32_e32 v80, v6
	v_mul_f32_e32 v6, 0xbfb8aa3b, v9
	v_exp_f32_e32 v81, v6
	v_cvt_pk_bf16_f32 v134, v135, v136
	s_addc_u32 s29, s29, 0
	s_add_u32 s34, s34, 0x100000
	s_addc_u32 s35, s35, 0
	s_cmp_lg_u32 s3, 3
	v_add_f32_e32 v2, 1.0, v80
	v_rcp_f32_e32 v80, v2
	v_add_f32_e32 v2, 1.0, v81
	v_rcp_f32_e32 v81, v2
	v_mul_f32_e32 v2, 0xbfb8aa3b, v10
	v_exp_f32_e32 v10, v2
	v_mul_f32_e32 v0, 0xbfb8aa3b, v11
	v_exp_f32_e32 v0, v0
	v_add_f32_e32 v10, 1.0, v10
	v_rcp_f32_e32 v10, v10
	v_cvt_pk_bf16_f32 v11, v80, v81
	v_add_f32_e32 v0, 1.0, v0
	v_rcp_f32_e32 v0, v0
	v_mul_f32_e32 v7, 0xbfb8aa3b, v13
	v_exp_f32_e32 v6, v12
	v_exp_f32_e32 v7, v7
	v_mul_f32_e32 v8, 0xbfb8aa3b, v14
	v_mul_f32_e32 v9, 0xbfb8aa3b, v15
	v_exp_f32_e32 v8, v8
	v_exp_f32_e32 v9, v9
	v_mul_f32_e32 v12, 0xbfb8aa3b, v16
	v_mul_f32_e32 v13, 0xbfb8aa3b, v17
	v_add_f32_e32 v6, 1.0, v6
	v_add_f32_e32 v7, 1.0, v7
	v_exp_f32_e32 v12, v12
	v_exp_f32_e32 v13, v13
	v_rcp_f32_e32 v6, v6
	v_rcp_f32_e32 v7, v7
	v_add_f32_e32 v8, 1.0, v8
	v_add_f32_e32 v9, 1.0, v9
	v_rcp_f32_e32 v8, v8
	v_rcp_f32_e32 v9, v9
	v_cvt_pk_bf16_f32 v0, v10, v0
	v_add_f32_e32 v12, 1.0, v12
	v_lshlrev_b32_e32 v2, 16, v201
	v_lshlrev_b32_e32 v4, 16, v66
	v_and_b32_e32 v3, 0xffff0000, v201
	v_and_b32_e32 v5, 0xffff0000, v66
	v_fma_f32 v2, v114, v4, v2
	v_fma_f32 v3, v115, v5, v3
	v_lshlrev_b32_e32 v4, 16, v67
	v_cvt_pk_bf16_f32 v201, v2, v3
	v_lshlrev_b32_e32 v2, 16, v200
	v_and_b32_e32 v3, 0xffff0000, v200
	v_and_b32_e32 v5, 0xffff0000, v67
	v_pk_fma_f32 v[2:3], v[116:117], v[4:5], v[2:3]
	v_lshlrev_b32_e32 v4, 16, v68
	v_cvt_pk_bf16_f32 v200, v2, v3
	v_lshlrev_b32_e32 v2, 16, v199
	v_and_b32_e32 v3, 0xffff0000, v199
	v_and_b32_e32 v5, 0xffff0000, v68
	v_pk_fma_f32 v[2:3], v[118:119], v[4:5], v[2:3]
	v_lshlrev_b32_e32 v4, 16, v69
	v_cvt_pk_bf16_f32 v199, v2, v3
	v_lshlrev_b32_e32 v2, 16, v196
	v_and_b32_e32 v3, 0xffff0000, v196
	v_and_b32_e32 v5, 0xffff0000, v69
	v_pk_fma_f32 v[2:3], v[120:121], v[4:5], v[2:3]
	v_lshlrev_b32_e32 v4, 16, v70
	v_cvt_pk_bf16_f32 v196, v2, v3
	v_lshlrev_b32_e32 v2, 16, v193
	v_and_b32_e32 v3, 0xffff0000, v193
	v_and_b32_e32 v5, 0xffff0000, v70
	v_fma_f32 v2, v122, v4, v2
	v_fma_f32 v3, v123, v5, v3
	v_lshlrev_b32_e32 v4, 16, v71
	v_cvt_pk_bf16_f32 v193, v2, v3
	v_lshlrev_b32_e32 v2, 16, v192
	v_and_b32_e32 v3, 0xffff0000, v192
	v_and_b32_e32 v5, 0xffff0000, v71
	v_pk_fma_f32 v[2:3], v[124:125], v[4:5], v[2:3]
	v_lshlrev_b32_e32 v4, 16, v72
	v_cvt_pk_bf16_f32 v192, v2, v3
	v_lshlrev_b32_e32 v2, 16, v191
	v_and_b32_e32 v3, 0xffff0000, v191
	v_and_b32_e32 v5, 0xffff0000, v72
	v_pk_fma_f32 v[2:3], v[126:127], v[4:5], v[2:3]
	v_lshlrev_b32_e32 v4, 16, v34
	v_cvt_pk_bf16_f32 v191, v2, v3
	v_lshlrev_b32_e32 v2, 16, v190
	v_and_b32_e32 v3, 0xffff0000, v190
	v_and_b32_e32 v5, 0xffff0000, v34
	v_pk_fma_f32 v[2:3], v[128:129], v[4:5], v[2:3]
	v_lshlrev_b32_e32 v4, 16, v35
	v_cvt_pk_bf16_f32 v190, v2, v3
	v_lshlrev_b32_e32 v2, 16, v187
	v_and_b32_e32 v3, 0xffff0000, v187
	v_and_b32_e32 v5, 0xffff0000, v35
	v_pk_fma_f32 v[2:3], v[98:99], v[4:5], v[2:3]
	v_lshlrev_b32_e32 v4, 16, v36
	v_cvt_pk_bf16_f32 v187, v2, v3
	v_lshlrev_b32_e32 v2, 16, v189
	v_and_b32_e32 v3, 0xffff0000, v189
	v_and_b32_e32 v5, 0xffff0000, v36
	v_pk_fma_f32 v[2:3], v[100:101], v[4:5], v[2:3]
	v_lshlrev_b32_e32 v4, 16, v37
	v_cvt_pk_bf16_f32 v189, v2, v3
	v_lshlrev_b32_e32 v2, 16, v188
	v_and_b32_e32 v3, 0xffff0000, v188
	v_and_b32_e32 v5, 0xffff0000, v37
	v_pk_fma_f32 v[2:3], v[102:103], v[4:5], v[2:3]
	v_lshlrev_b32_e32 v4, 16, v38
	v_cvt_pk_bf16_f32 v188, v2, v3
	v_lshlrev_b32_e32 v2, 16, v186
	v_and_b32_e32 v3, 0xffff0000, v186
	v_and_b32_e32 v5, 0xffff0000, v38
	v_pk_fma_f32 v[2:3], v[104:105], v[4:5], v[2:3]
	v_lshlrev_b32_e32 v4, 16, v39
	v_cvt_pk_bf16_f32 v186, v2, v3
	v_lshlrev_b32_e32 v2, 16, v185
	v_and_b32_e32 v3, 0xffff0000, v185
	v_and_b32_e32 v5, 0xffff0000, v39
	v_pk_fma_f32 v[2:3], v[106:107], v[4:5], v[2:3]
	v_lshlrev_b32_e32 v4, 16, v40
	v_cvt_pk_bf16_f32 v185, v2, v3
	v_lshlrev_b32_e32 v2, 16, v184
	v_and_b32_e32 v3, 0xffff0000, v184
	v_and_b32_e32 v5, 0xffff0000, v40
; __device__ __forceinline__ unsigned pack2(float a, float b) { f2_t f = {a, b}; return __builtin_bit_cast(unsigned, __builtin_convertvector(f, bf2_t)); }
; __device__ __forceinline__ void merge_tile(const Params& p, int mt, int nt, bf16* sA, bf16* sB) {
;     ...
; #pragma unroll
;     for (int mi = 0; mi < 2; ++mi)
; #pragma unroll
;       for (int ni = 0; ni < 2; ++ni)
; #pragma unroll
;         for (int e = 0; e < 8; ++e) {
;           const float v0 = __uint_as_float(mg[mi][ni][e] << 16) + __uint_as_float(sg[mi][ni][e] << 16) * ap[mi][ni][2 * e];
;           const float v1 = __uint_as_float(mg[mi][ni][e] & 0xffff0000u) + __uint_as_float(sg[mi][ni][e] & 0xffff0000u) * ap[mi][ni][2 * e + 1];
;           mg[mi][ni][e] = pack2(v0, v1);
;         }
;   }
; #pragma unroll
;   for (int mi = 0; mi < 2; ++mi)
; #pragma unroll
;     for (int ni = 0; ni < 2; ++ni)
; #pragma unroll
;       for (int e = 0; e < 16; ++e) {
;         const int t = m0 + wm * 64 + mi * 32 + ROW_OF(e, hh);
;         p.merged[(size_t)t * DM + n0 + wn * 64 + ni * 32 + r] = (bf16)((e & 1) ? (mg[mi][ni][e >> 1] >> 16) : (mg[mi][ni][e >> 1] & 0xffffu));
	v_pk_fma_f32 v[2:3], v[108:109], v[4:5], v[2:3]
	v_lshlrev_b32_e32 v4, 16, v41
	v_cvt_pk_bf16_f32 v184, v2, v3
	v_lshlrev_b32_e32 v2, 16, v183
	v_and_b32_e32 v3, 0xffff0000, v183
	v_and_b32_e32 v5, 0xffff0000, v41
	v_pk_fma_f32 v[2:3], v[110:111], v[4:5], v[2:3]
	v_lshlrev_b32_e32 v4, 16, v18
	v_cvt_pk_bf16_f32 v183, v2, v3
	v_lshlrev_b32_e32 v2, 16, v182
	v_and_b32_e32 v3, 0xffff0000, v182
	v_and_b32_e32 v5, 0xffff0000, v18
	v_pk_fma_f32 v[2:3], v[112:113], v[4:5], v[2:3]
	v_lshlrev_b32_e32 v4, 16, v19
	v_cvt_pk_bf16_f32 v182, v2, v3
	v_lshlrev_b32_e32 v2, 16, v181
	v_and_b32_e32 v3, 0xffff0000, v181
	v_and_b32_e32 v5, 0xffff0000, v19
	v_pk_fma_f32 v[2:3], v[82:83], v[4:5], v[2:3]
	v_lshlrev_b32_e32 v4, 16, v20
	v_cvt_pk_bf16_f32 v181, v2, v3
	v_lshlrev_b32_e32 v2, 16, v180
	v_and_b32_e32 v3, 0xffff0000, v180
	v_and_b32_e32 v5, 0xffff0000, v20
	v_pk_fma_f32 v[2:3], v[84:85], v[4:5], v[2:3]
	v_lshlrev_b32_e32 v4, 16, v21
	v_cvt_pk_bf16_f32 v180, v2, v3
	v_lshlrev_b32_e32 v2, 16, v179
	v_and_b32_e32 v3, 0xffff0000, v179
	v_and_b32_e32 v5, 0xffff0000, v21
	v_pk_fma_f32 v[2:3], v[86:87], v[4:5], v[2:3]
	v_lshlrev_b32_e32 v4, 16, v22
	v_cvt_pk_bf16_f32 v179, v2, v3
	v_lshlrev_b32_e32 v2, 16, v178
	v_and_b32_e32 v3, 0xffff0000, v178
	v_and_b32_e32 v5, 0xffff0000, v22
	v_pk_fma_f32 v[2:3], v[88:89], v[4:5], v[2:3]
	v_lshlrev_b32_e32 v4, 16, v23
	v_cvt_pk_bf16_f32 v178, v2, v3
	v_lshlrev_b32_e32 v2, 16, v177
	v_and_b32_e32 v3, 0xffff0000, v177
	v_and_b32_e32 v5, 0xffff0000, v23
	v_pk_fma_f32 v[2:3], v[90:91], v[4:5], v[2:3]
	v_lshlrev_b32_e32 v4, 16, v73
	v_cvt_pk_bf16_f32 v177, v2, v3
	v_lshlrev_b32_e32 v2, 16, v176
	v_and_b32_e32 v3, 0xffff0000, v176
	v_and_b32_e32 v5, 0xffff0000, v73
	v_pk_fma_f32 v[2:3], v[92:93], v[4:5], v[2:3]
	v_lshlrev_b32_e32 v4, 16, v134
	v_cvt_pk_bf16_f32 v176, v2, v3
	v_lshlrev_b32_e32 v2, 16, v175
	v_and_b32_e32 v3, 0xffff0000, v175
	v_and_b32_e32 v5, 0xffff0000, v134
	v_pk_fma_f32 v[2:3], v[94:95], v[4:5], v[2:3]
	v_lshlrev_b32_e32 v4, 16, v32
	v_cvt_pk_bf16_f32 v175, v2, v3
	v_lshlrev_b32_e32 v2, 16, v174
	v_and_b32_e32 v3, 0xffff0000, v174
	v_and_b32_e32 v5, 0xffff0000, v32
	v_pk_fma_f32 v[2:3], v[96:97], v[4:5], v[2:3]
	v_lshlrev_b32_e32 v4, 16, v33
	v_cvt_pk_bf16_f32 v174, v2, v3
	v_lshlrev_b32_e32 v2, 16, v170
	v_and_b32_e32 v3, 0xffff0000, v170
	v_and_b32_e32 v5, 0xffff0000, v33
	v_pk_fma_f32 v[2:3], v[50:51], v[4:5], v[2:3]
	v_lshlrev_b32_e32 v4, 16, v78
	v_cvt_pk_bf16_f32 v170, v2, v3
	v_lshlrev_b32_e32 v2, 16, v172
	v_and_b32_e32 v3, 0xffff0000, v172
	v_and_b32_e32 v5, 0xffff0000, v78
	v_pk_fma_f32 v[2:3], v[52:53], v[4:5], v[2:3]
	v_lshlrev_b32_e32 v4, 16, v79
	v_cvt_pk_bf16_f32 v172, v2, v3
	v_lshlrev_b32_e32 v2, 16, v171
	v_and_b32_e32 v3, 0xffff0000, v171
	v_and_b32_e32 v5, 0xffff0000, v79
	v_pk_fma_f32 v[2:3], v[54:55], v[4:5], v[2:3]
	v_lshlrev_b32_e32 v4, 16, v11
	v_cvt_pk_bf16_f32 v171, v2, v3
	v_lshlrev_b32_e32 v2, 16, v169
	v_and_b32_e32 v3, 0xffff0000, v169
	v_and_b32_e32 v5, 0xffff0000, v11
	v_pk_fma_f32 v[2:3], v[56:57], v[4:5], v[2:3]
	v_add_f32_e32 v13, 1.0, v13
	v_cvt_pk_bf16_f32 v169, v2, v3
	v_lshlrev_b32_e32 v2, 16, v168
	v_lshlrev_b32_e32 v4, 16, v0
	v_and_b32_e32 v3, 0xffff0000, v168
	v_and_b32_e32 v5, 0xffff0000, v0
	v_rcp_f32_e32 v12, v12
	v_rcp_f32_e32 v13, v13
	v_cvt_pk_bf16_f32 v6, v6, v7
	v_pk_fma_f32 v[2:3], v[58:59], v[4:5], v[2:3]
	v_lshlrev_b32_e32 v4, 16, v6
	v_cvt_pk_bf16_f32 v168, v2, v3
	v_lshlrev_b32_e32 v2, 16, v167
	v_and_b32_e32 v3, 0xffff0000, v167
	v_and_b32_e32 v5, 0xffff0000, v6
	v_cvt_pk_bf16_f32 v7, v8, v9
	v_pk_fma_f32 v[2:3], v[60:61], v[4:5], v[2:3]
	v_lshlrev_b32_e32 v4, 16, v7
	v_cvt_pk_bf16_f32 v167, v2, v3
	v_lshlrev_b32_e32 v2, 16, v166
	v_and_b32_e32 v3, 0xffff0000, v166
	v_and_b32_e32 v5, 0xffff0000, v7
	v_cvt_pk_bf16_f32 v8, v12, v13
	v_pk_fma_f32 v[2:3], v[62:63], v[4:5], v[2:3]
	v_lshlrev_b32_e32 v4, 16, v8
	v_cvt_pk_bf16_f32 v166, v2, v3
	v_lshlrev_b32_e32 v2, 16, v173
	v_and_b32_e32 v3, 0xffff0000, v173
	v_and_b32_e32 v5, 0xffff0000, v8
	v_pk_fma_f32 v[2:3], v[64:65], v[4:5], v[2:3]
	s_nop 0
	v_cvt_pk_bf16_f32 v173, v2, v3
	s_cbranch_scc1 .LBB0_1067
	v_lshrrev_b32_e32 v4, 3, v197
	v_ashrrev_i32_e32 v2, 1, v198
	v_and_or_b32 v4, v4, 4, s2
	s_lshl_b64 s[2:3], s[20:21], 1
	v_readlane_b32 s20, v252, 15
	v_and_b32_e32 v2, 0xffffffc0, v2
	v_readlane_b32 s26, v252, 21
	v_and_b32_e32 v0, 64, v198
	v_add_u32_e32 v2, v4, v2
	v_readlane_b32 s27, v252, 22
	s_add_u32 s2, s26, s2
	v_and_b32_e32 v3, 31, v197
	s_addc_u32 s3, s27, s3
	v_lshlrev_b32_e32 v0, 1, v0
	v_or_b32_e32 v8, 1, v2
	v_or_b32_e32 v10, 2, v2
	v_or_b32_e32 v12, 3, v2
	v_or_b32_e32 v14, 8, v2
	v_or_b32_e32 v16, 9, v2
	v_or_b32_e32 v18, 10, v2
	v_or_b32_e32 v20, 11, v2
	v_or_b32_e32 v22, 16, v2
	v_or_b32_e32 v24, 17, v2
	v_or_b32_e32 v26, 18, v2
	v_or_b32_e32 v28, 19, v2
	v_or_b32_e32 v30, 24, v2
	v_or_b32_e32 v32, 25, v2
	v_or_b32_e32 v34, 26, v2
	v_or_b32_e32 v36, 27, v2
	v_lshl_add_u64 v[4:5], s[2:3], 0, v[0:1]
	v_lshlrev_b32_e32 v0, 1, v3
	v_ashrrev_i32_e32 v3, 31, v2
	v_ashrrev_i32_e32 v9, 31, v8
	v_ashrrev_i32_e32 v11, 31, v10
	v_ashrrev_i32_e32 v13, 31, v12
	v_ashrrev_i32_e32 v15, 31, v14
	v_ashrrev_i32_e32 v17, 31, v16
	v_ashrrev_i32_e32 v19, 31, v18
	v_ashrrev_i32_e32 v21, 31, v20
	v_ashrrev_i32_e32 v23, 31, v22
	v_ashrrev_i32_e32 v25, 31, v24
	v_ashrrev_i32_e32 v27, 31, v26
	v_ashrrev_i32_e32 v29, 31, v28
	v_ashrrev_i32_e32 v31, 31, v30
	v_ashrrev_i32_e32 v33, 31, v32
	v_ashrrev_i32_e32 v35, 31, v34
	v_ashrrev_i32_e32 v37, 31, v36
	v_lshl_add_u64 v[4:5], v[4:5], 0, v[0:1]
	v_lshlrev_b64 v[6:7], 11, v[2:3]
	v_lshlrev_b64 v[8:9], 11, v[8:9]
	v_lshlrev_b64 v[10:11], 11, v[10:11]
; __device__ __forceinline__ void merge_tile(const Params& p, int mt, int nt, bf16* sA, bf16* sB) {
;     ...
; #pragma unroll
;   for (int mi = 0; mi < 2; ++mi)
; #pragma unroll
;     for (int ni = 0; ni < 2; ++ni)
; #pragma unroll
;       for (int e = 0; e < 16; ++e) {
;         const int t = m0 + wm * 64 + mi * 32 + ROW_OF(e, hh);
;         p.merged[(size_t)t * DM + n0 + wn * 64 + ni * 32 + r] = (bf16)((e & 1) ? (mg[mi][ni][e >> 1] >> 16) : (mg[mi][ni][e >> 1] & 0xffffu));
;       }
	v_lshlrev_b64 v[12:13], 11, v[12:13]
	v_lshlrev_b64 v[14:15], 11, v[14:15]
	v_lshlrev_b64 v[16:17], 11, v[16:17]
	v_lshlrev_b64 v[18:19], 11, v[18:19]
	v_lshlrev_b64 v[20:21], 11, v[20:21]
	v_lshlrev_b64 v[22:23], 11, v[22:23]
	v_lshlrev_b64 v[24:25], 11, v[24:25]
	v_lshlrev_b64 v[26:27], 11, v[26:27]
	v_lshlrev_b64 v[28:29], 11, v[28:29]
	v_lshlrev_b64 v[30:31], 11, v[30:31]
	v_lshlrev_b64 v[32:33], 11, v[32:33]
	v_lshlrev_b64 v[34:35], 11, v[34:35]
	v_lshlrev_b64 v[36:37], 11, v[36:37]
	v_lshl_add_u64 v[6:7], v[4:5], 0, v[6:7]
	v_lshl_add_u64 v[8:9], v[4:5], 0, v[8:9]
	v_lshl_add_u64 v[10:11], v[4:5], 0, v[10:11]
	v_lshl_add_u64 v[12:13], v[4:5], 0, v[12:13]
	v_lshl_add_u64 v[14:15], v[4:5], 0, v[14:15]
	v_lshl_add_u64 v[16:17], v[4:5], 0, v[16:17]
	v_lshl_add_u64 v[18:19], v[4:5], 0, v[18:19]
	v_lshl_add_u64 v[20:21], v[4:5], 0, v[20:21]
	v_lshl_add_u64 v[22:23], v[4:5], 0, v[22:23]
	v_lshl_add_u64 v[24:25], v[4:5], 0, v[24:25]
	v_lshl_add_u64 v[26:27], v[4:5], 0, v[26:27]
	v_lshl_add_u64 v[28:29], v[4:5], 0, v[28:29]
	v_lshl_add_u64 v[30:31], v[4:5], 0, v[30:31]
	v_lshl_add_u64 v[32:33], v[4:5], 0, v[32:33]
	v_lshl_add_u64 v[34:35], v[4:5], 0, v[34:35]
	v_lshl_add_u64 v[36:37], v[4:5], 0, v[36:37]
	global_store_short v[6:7], v201, off
	global_store_short_d16_hi v[8:9], v201, off
	global_store_short v[10:11], v200, off
	global_store_short_d16_hi v[12:13], v200, off
	global_store_short v[14:15], v199, off
	global_store_short_d16_hi v[16:17], v199, off
	global_store_short v[18:19], v196, off
	global_store_short_d16_hi v[20:21], v196, off
	global_store_short v[22:23], v193, off
	global_store_short_d16_hi v[24:25], v193, off
	global_store_short v[26:27], v192, off
	global_store_short_d16_hi v[28:29], v192, off
	global_store_short v[30:31], v191, off
	global_store_short_d16_hi v[32:33], v191, off
	global_store_short v[34:35], v190, off
	global_store_short_d16_hi v[36:37], v190, off
	global_store_short v[6:7], v187, off offset:64
	global_store_short_d16_hi v[8:9], v187, off offset:64
	global_store_short v[10:11], v189, off offset:64
	global_store_short_d16_hi v[12:13], v189, off offset:64
	global_store_short v[14:15], v188, off offset:64
	global_store_short_d16_hi v[16:17], v188, off offset:64
	global_store_short v[18:19], v186, off offset:64
	global_store_short_d16_hi v[20:21], v186, off offset:64
	global_store_short v[22:23], v185, off offset:64
	global_store_short_d16_hi v[24:25], v185, off offset:64
	global_store_short v[26:27], v184, off offset:64
	global_store_short_d16_hi v[28:29], v184, off offset:64
	global_store_short v[30:31], v183, off offset:64
	global_store_short_d16_hi v[32:33], v183, off offset:64
	global_store_short v[34:35], v182, off offset:64
	global_store_short_d16_hi v[36:37], v182, off offset:64
	v_or_b32_e32 v6, 32, v2
	v_or_b32_e32 v8, 33, v2
	v_or_b32_e32 v10, 34, v2
	v_or_b32_e32 v12, 35, v2
	v_or_b32_e32 v14, 40, v2
	v_or_b32_e32 v16, 41, v2
	v_or_b32_e32 v18, 42, v2
	v_or_b32_e32 v20, 43, v2
	v_or_b32_e32 v22, 48, v2
	v_or_b32_e32 v24, 49, v2
	v_or_b32_e32 v26, 50, v2
	v_or_b32_e32 v28, 51, v2
	v_or_b32_e32 v30, 56, v2
	v_or_b32_e32 v32, 57, v2
	v_or_b32_e32 v34, 58, v2
	v_or_b32_e32 v2, 59, v2
	v_ashrrev_i32_e32 v7, 31, v6
	v_ashrrev_i32_e32 v9, 31, v8
	v_ashrrev_i32_e32 v11, 31, v10
	v_ashrrev_i32_e32 v13, 31, v12
	v_ashrrev_i32_e32 v15, 31, v14
	v_ashrrev_i32_e32 v17, 31, v16
	v_ashrrev_i32_e32 v19, 31, v18
	v_ashrrev_i32_e32 v21, 31, v20
	v_ashrrev_i32_e32 v23, 31, v22
	v_ashrrev_i32_e32 v25, 31, v24
	v_ashrrev_i32_e32 v27, 31, v26
	v_ashrrev_i32_e32 v29, 31, v28
	v_ashrrev_i32_e32 v31, 31, v30
	v_ashrrev_i32_e32 v33, 31, v32
	v_ashrrev_i32_e32 v35, 31, v34
	v_ashrrev_i32_e32 v3, 31, v2
	v_readlane_b32 s2, v254, 60
	v_lshlrev_b64 v[6:7], 11, v[6:7]
	v_lshlrev_b64 v[8:9], 11, v[8:9]
	v_lshlrev_b64 v[10:11], 11, v[10:11]
	v_lshlrev_b64 v[12:13], 11, v[12:13]
	v_lshlrev_b64 v[14:15], 11, v[14:15]
	v_lshlrev_b64 v[16:17], 11, v[16:17]
	v_lshlrev_b64 v[18:19], 11, v[18:19]
	v_lshlrev_b64 v[20:21], 11, v[20:21]
	v_lshlrev_b64 v[22:23], 11, v[22:23]
	v_lshlrev_b64 v[24:25], 11, v[24:25]
	v_lshlrev_b64 v[26:27], 11, v[26:27]
	v_lshlrev_b64 v[28:29], 11, v[28:29]
	v_lshlrev_b64 v[30:31], 11, v[30:31]
	v_lshlrev_b64 v[32:33], 11, v[32:33]
	v_lshlrev_b64 v[34:35], 11, v[34:35]
	v_lshlrev_b64 v[2:3], 11, v[2:3]
	s_add_i32 s0, s0, s2
	v_lshl_add_u64 v[6:7], v[4:5], 0, v[6:7]
	v_lshl_add_u64 v[8:9], v[4:5], 0, v[8:9]
	v_lshl_add_u64 v[10:11], v[4:5], 0, v[10:11]
	v_lshl_add_u64 v[12:13], v[4:5], 0, v[12:13]
	v_lshl_add_u64 v[14:15], v[4:5], 0, v[14:15]
	v_lshl_add_u64 v[16:17], v[4:5], 0, v[16:17]
	v_lshl_add_u64 v[18:19], v[4:5], 0, v[18:19]
	v_lshl_add_u64 v[20:21], v[4:5], 0, v[20:21]
	v_lshl_add_u64 v[22:23], v[4:5], 0, v[22:23]
	v_lshl_add_u64 v[24:25], v[4:5], 0, v[24:25]
	v_lshl_add_u64 v[26:27], v[4:5], 0, v[26:27]
	v_lshl_add_u64 v[28:29], v[4:5], 0, v[28:29]
	v_lshl_add_u64 v[30:31], v[4:5], 0, v[30:31]
	v_lshl_add_u64 v[32:33], v[4:5], 0, v[32:33]
	v_lshl_add_u64 v[34:35], v[4:5], 0, v[34:35]
	v_lshl_add_u64 v[2:3], v[4:5], 0, v[2:3]
	s_cmpk_gt_u32 s0, 0xff
	v_readlane_b32 s21, v252, 16
	v_readlane_b32 s22, v252, 17
	v_readlane_b32 s23, v252, 18
	v_readlane_b32 s24, v252, 19
	v_readlane_b32 s25, v252, 20
	global_store_short v[6:7], v181, off
	global_store_short_d16_hi v[8:9], v181, off
	global_store_short v[10:11], v180, off
	global_store_short_d16_hi v[12:13], v180, off
	global_store_short v[14:15], v179, off
	global_store_short_d16_hi v[16:17], v179, off
	global_store_short v[18:19], v178, off
	global_store_short_d16_hi v[20:21], v178, off
	global_store_short v[22:23], v177, off
	global_store_short_d16_hi v[24:25], v177, off
	global_store_short v[26:27], v176, off
	global_store_short_d16_hi v[28:29], v176, off
	global_store_short v[30:31], v175, off
	global_store_short_d16_hi v[32:33], v175, off
	global_store_short v[34:35], v174, off
	global_store_short_d16_hi v[2:3], v174, off
	global_store_short v[6:7], v170, off offset:64
	global_store_short_d16_hi v[8:9], v170, off offset:64
	global_store_short v[10:11], v172, off offset:64
	global_store_short_d16_hi v[12:13], v172, off offset:64
	global_store_short v[14:15], v171, off offset:64
	global_store_short_d16_hi v[16:17], v171, off offset:64
	global_store_short v[18:19], v169, off offset:64
	global_store_short_d16_hi v[20:21], v169, off offset:64
	global_store_short v[22:23], v168, off offset:64
	global_store_short_d16_hi v[24:25], v168, off offset:64
	global_store_short v[26:27], v167, off offset:64
	global_store_short_d16_hi v[28:29], v167, off offset:64
	global_store_short v[30:31], v166, off offset:64
	global_store_short_d16_hi v[32:33], v166, off offset:64
	global_store_short v[34:35], v173, off offset:64
	global_store_short_d16_hi v[2:3], v173, off offset:64
	s_cbranch_scc0 .LBB0_1066
